# attention: hand-scheduled fast path for unmasked KV tiles (K fragments read up front, QK split by row block so max trees run in MFMA shadow, v_max3 trees)
# speedup vs baseline: 1.0246x; 1.0098x over previous
; #define LAS __attribute__((address_space(3)))
; __device__ __forceinline__ void unit(unsigned char* ws, LAS unsigned char* lds, int b, int h, int mp, int qb, const int tid_in) {
;     ...
;         if (k0 <= qw0 + 31) {
;         f32x4 s[2][4];
; #pragma unroll
;         for (int jt = 0; jt < 4; ++jt) { const bf16x8 kf0 = *(const LAS bf16x8*)(KS + (16 * jt + fr) * KP + 8 * fq), kf1 = *(const LAS bf16x8*)(KS + (16 * jt + fr) * KP + 32 + 8 * fq);
; #pragma unroll
;             for (int g = 0; g < 2; ++g) { const float nm = -m[g]; s[g][jt] = __builtin_amdgcn_mfma_f32_16x16x32_bf16(kf0, qf[g][0], (f32x4){nm, nm, nm, nm}, 0, 0, 0); s[g][jt] = __builtin_amdgcn_mfma_f32_16x16x32_bf16(kf1, qf[g][1], s[g][jt], 0, 0, 0); } }
;         const bool nearb = (qw0 - (k0 + 63) < 113);
.LBB0_183:
	s_cmpk_gt_i32 s81, 0x70
	s_cbranch_scc1 .Lattn_fast
	s_bitcmp1_b32 s68, 0
	s_cselect_b32 s21, 0, 0x6c00
	v_add_u32_e32 v179, s21, v174
	v_lshl_add_u32 v178, v169, 1, v179
	ds_read_b128 v[114:117], v178
	ds_read_b128 v[118:121], v178 offset:64
	v_xor_b32_e32 v134, 0x80000000, v175
	v_mov_b32_e32 v135, v134
	v_mov_b32_e32 v136, v134
	v_mov_b32_e32 v137, v134
	v_xor_b32_e32 v180, 0x80000000, v177
	v_mov_b32_e32 v181, v180
	v_mov_b32_e32 v182, v180
	s_waitcnt lgkmcnt(1)
	v_mfma_f32_16x16x32_bf16 v[122:125], v[114:117], v[82:85], v[134:137]
	v_mov_b32_e32 v183, v180
	ds_read_b128 v[142:145], v178 offset:4608
	ds_read_b128 v[198:201], v178 offset:6912
	ds_read_b128 v[202:205], v178 offset:6976
	s_nop 0
	v_mfma_f32_16x16x32_bf16 v[114:117], v[114:117], v[86:89], v[180:183]
	s_cmpk_gt_i32 s81, 0x70
	s_cselect_b64 s[22:23], -1, 0
	s_cmpk_lt_i32 s81, 0x71
	s_waitcnt lgkmcnt(3)
	v_mfma_f32_16x16x32_bf16 v[126:129], v[118:121], v[78:81], v[122:125]
	s_mov_b64 s[60:61], -1
	s_nop 1
	ds_read_b128 v[122:125], v178 offset:2304
	s_nop 0
	v_mfma_f32_16x16x32_bf16 v[114:117], v[118:121], v[74:77], v[114:117]
	ds_read_b128 v[118:121], v178 offset:2368
	s_waitcnt lgkmcnt(1)
	v_mfma_f32_16x16x32_bf16 v[130:133], v[122:125], v[82:85], v[134:137]
	v_mfma_f32_16x16x32_bf16 v[122:125], v[122:125], v[86:89], v[180:183]
	s_waitcnt lgkmcnt(0)
	v_mfma_f32_16x16x32_bf16 v[130:133], v[118:121], v[78:81], v[130:133]
	v_mfma_f32_16x16x32_bf16 v[118:121], v[118:121], v[74:77], v[122:125]
	s_nop 4
	ds_read_b128 v[122:125], v178 offset:4672
	v_mfma_f32_16x16x32_bf16 v[138:141], v[142:145], v[82:85], v[134:137]
	v_mfma_f32_16x16x32_bf16 v[142:145], v[142:145], v[86:89], v[180:183]
	v_mfma_f32_16x16x32_bf16 v[134:137], v[198:201], v[82:85], v[134:137]
	s_waitcnt lgkmcnt(0)
	v_mfma_f32_16x16x32_bf16 v[138:141], v[122:125], v[78:81], v[138:141]
	v_mfma_f32_16x16x32_bf16 v[122:125], v[122:125], v[74:77], v[142:145]
	v_mfma_f32_16x16x32_bf16 v[142:145], v[202:205], v[78:81], v[134:137]
	v_mfma_f32_16x16x32_bf16 v[134:137], v[198:201], v[86:89], v[180:183]
	v_mfma_f32_16x16x32_bf16 v[134:137], v[202:205], v[74:77], v[134:137]
	s_cbranch_scc1 .LBB0_185
	s_mov_b64 s[60:61], 0

; __device__ __forceinline__ void unit(unsigned char* ws, LAS unsigned char* lds, int b, int h, int mp, int qb, const int tid_in) {
;     ...
;         for (int jt = 0; jt < 4; ++jt) { const bf16x8 kf0 = *(const LAS bf16x8*)(KS + (16 * jt + fr) * KP + 8 * fq), kf1 = *(const LAS bf16x8*)(KS + (16 * jt + fr) * KP + 32 + 8 * fq);
; #pragma unroll
;             for (int g = 0; g < 2; ++g) { const float nm = -m[g]; s[g][jt] = __builtin_amdgcn_mfma_f32_16x16x32_bf16(kf0, qf[g][0], (f32x4){nm, nm, nm, nm}, 0, 0, 0); s[g][jt] = __builtin_amdgcn_mfma_f32_16x16x32_bf16(kf1, qf[g][1], s[g][jt], 0, 0, 0); } }
;         const bool nearb = (qw0 - (k0 + 63) < 113);
;         bf16x8 pf[2][2];
; #pragma unroll
;         for (int g = 0; g < 2; ++g) {
;             if (nearb) {
;                 const LAS float* tb = TB + (256 + qw0 + 16 * g + fr - (k0 + 4 * fq));
; #pragma unroll
;                 for (int jt = 0; jt < 4; ++jt)
; #pragma unroll
;                     for (int jj = 0; jj < 4; ++jj) { const float bv = tb[-(16 * jt + jj)]; float x = s[g][jt][jj];
;                         asm("v_add_f32_e32 %0, %1, %2" : "=v"(x) : "v"(x), "v"(bv));
;                         s[g][jt][jj] = x; }
;             }
;             float mx = fmaxf(fmaxf(s[g][0][0], s[g][0][1]), fmaxf(s[g][0][2], s[g][0][3]));
; #pragma unroll
;             for (int jt = 1; jt < 4; ++jt) mx = fmaxf(mx, fmaxf(fmaxf(s[g][jt][0], s[g][jt][1]), fmaxf(s[g][jt][2], s[g][jt][3])));
;             if (__any(mx > 8.f)) {
;                 mx = fmaxf(mx, __shfl_xor(mx, 16)); mx = fmaxf(mx, __shfl_xor(mx, 32));
;                 const float dl = fmaxf(mx, 0.f), alpha = __builtin_amdgcn_exp2f(-dl);
;                 m[g] += dl; lacc[g] *= alpha;
; #pragma unroll
;                 for (int jt = 0; jt < 4; ++jt) s[g][jt] -= dl;
; #pragma unroll
;                 for (int et = 0; et < 8; ++et) o[g][et] *= alpha;
;             }
; #pragma unroll
;             for (int jt = 0; jt < 4; ++jt) {
; #pragma unroll
;                 for (int jj = 0; jj < 4; ++jj) s[g][jt][jj] = __builtin_amdgcn_exp2f(s[g][jt][jj]); }
; #pragma unroll
;             for (int sb = 0; sb < 2; ++sb) { u32x4 pw; pw.x = cvtpk(s[g][2 * sb][0], s[g][2 * sb][1]); pw.y = cvtpk(s[g][2 * sb][2], s[g][2 * sb][3]); pw.z = cvtpk(s[g][2 * sb + 1][0], s[g][2 * sb + 1][1]); pw.w = cvtpk(s[g][2 * sb + 1][2], s[g][2 * sb + 1][3]);
.Lattn_fast:
	s_bitcmp1_b32 s68, 0
	s_cselect_b32 s21, 0, 0x6c00
	v_add_u32_e32 v179, s21, v174
	v_lshl_add_u32 v178, v169, 1, v179
	ds_read_b128 v[222:225], v178
	ds_read_b128 v[226:229], v178 offset:64
	ds_read_b128 v[230:233], v178 offset:2304
	ds_read_b128 v[234:237], v178 offset:2368
	ds_read_b128 v[238:241], v178 offset:4608
	ds_read_b128 v[242:245], v178 offset:4672
	ds_read_b128 v[246:249], v178 offset:6912
	ds_read_b128 v[250:253], v178 offset:6976
	v_xor_b32_e32 v214, 0x80000000, v175
	v_mov_b32_e32 v215, v214
	v_mov_b32_e32 v216, v214
	v_mov_b32_e32 v217, v214
	v_xor_b32_e32 v218, 0x80000000, v177
	v_mov_b32_e32 v219, v218
	v_mov_b32_e32 v220, v218
	v_mov_b32_e32 v221, v218
	s_waitcnt lgkmcnt(7)
	v_mfma_f32_16x16x32_bf16 v[126:129], v[222:225], v[82:85], v[214:217]
	v_lshl_add_u32 v210, v168, 1, v179
	s_waitcnt lgkmcnt(6)
	v_mfma_f32_16x16x32_bf16 v[126:129], v[226:229], v[78:81], v[126:129]
	v_lshl_add_u32 v211, v167, 1, v179
	s_waitcnt lgkmcnt(5)
	v_mfma_f32_16x16x32_bf16 v[130:133], v[230:233], v[82:85], v[214:217]
	v_lshl_add_u32 v212, v166, 1, v179
	s_waitcnt lgkmcnt(4)
	v_mfma_f32_16x16x32_bf16 v[130:133], v[234:237], v[78:81], v[130:133]
	v_mov_b32_e32 v206, s20
	s_waitcnt lgkmcnt(3)
	v_mfma_f32_16x16x32_bf16 v[138:141], v[238:241], v[82:85], v[214:217]
	v_mov_b32_e32 v207, s20
	s_waitcnt lgkmcnt(2)
	v_mfma_f32_16x16x32_bf16 v[138:141], v[242:245], v[78:81], v[138:141]
	v_mov_b32_e32 v208, s20
	s_waitcnt lgkmcnt(1)
	v_mfma_f32_16x16x32_bf16 v[142:145], v[246:249], v[82:85], v[214:217]
	v_mov_b32_e32 v209, s20
	s_waitcnt lgkmcnt(0)
	v_mfma_f32_16x16x32_bf16 v[142:145], v[250:253], v[78:81], v[142:145]
	v_mfma_f32_16x16x32_bf16 v[114:117], v[222:225], v[86:89], v[218:221]
	v_mfma_f32_16x16x32_bf16 v[114:117], v[226:229], v[74:77], v[114:117]
	v_max3_f32 v181, v126, v127, v128
	v_mfma_f32_16x16x32_bf16 v[118:121], v[230:233], v[86:89], v[218:221]
	v_max3_f32 v182, v129, v130, v131
	v_mfma_f32_16x16x32_bf16 v[118:121], v[234:237], v[74:77], v[118:121]
	v_max3_f32 v181, v132, v133, v181
	v_mfma_f32_16x16x32_bf16 v[122:125], v[238:241], v[86:89], v[218:221]
	v_max3_f32 v183, v138, v139, v140
	v_mfma_f32_16x16x32_bf16 v[122:125], v[242:245], v[74:77], v[122:125]
	v_max3_f32 v181, v141, v182, v181
	v_mfma_f32_16x16x32_bf16 v[134:137], v[246:249], v[86:89], v[218:221]
	v_mfma_f32_16x16x32_bf16 v[134:137], v[250:253], v[74:77], v[134:137]
	v_max3_f32 v182, v142, v143, v144
	v_max3_f32 v181, v145, v183, v181
	v_max_f32_e32 v180, v182, v181
	v_cmp_lt_f32_e32 vcc, s94, v180
	s_cbranch_vccnz .Lattn_rare0
.Lattn_back0:
	ds_read_b128 v[222:225], v178 offset:9216
	ds_read_b128 v[226:229], v178 offset:11536
	ds_read_b128 v[230:233], v178 offset:13856
	ds_read_b128 v[234:237], v178 offset:16176
	ds_read_b128 v[238:241], v178 offset:18496
	ds_read_b128 v[242:245], v210 offset:20736
	ds_read_b128 v[246:249], v211 offset:23040
	ds_read_b128 v[250:253], v212 offset:25344
	v_exp_f32_e32 v126, v126
	v_exp_f32_e32 v127, v127
	v_exp_f32_e32 v128, v128
	v_exp_f32_e32 v129, v129
	v_exp_f32_e32 v130, v130
	v_exp_f32_e32 v131, v131
	v_exp_f32_e32 v132, v132
	v_exp_f32_e32 v133, v133
	v_cvt_pk_bf16_f32 v126, v126, v127
	v_cvt_pk_bf16_f32 v127, v128, v129
	v_cvt_pk_bf16_f32 v128, v130, v131
	v_cvt_pk_bf16_f32 v129, v132, v133
	s_nop 1
	v_mfma_f32_16x16x32_bf16 v[70:73], v[206:209], v[126:129], v[70:73]
	v_max3_f32 v181, v114, v115, v116
	v_max3_f32 v182, v117, v118, v119
	v_max3_f32 v181, v120, v121, v181
	s_waitcnt lgkmcnt(7)
	v_mfma_f32_16x16x32_bf16 v[66:69], v[222:225], v[126:129], v[66:69]
	v_max3_f32 v183, v122, v123, v124
	v_max3_f32 v181, v125, v182, v181
	v_max3_f32 v182, v134, v135, v136
	s_waitcnt lgkmcnt(6)
	v_mfma_f32_16x16x32_bf16 v[62:65], v[226:229], v[126:129], v[62:65]
	v_max3_f32 v181, v137, v183, v181
	v_max_f32_e32 v180, v182, v181
	v_cmp_lt_f32_e32 vcc, s94, v180
	s_cbranch_vccnz .Lattn_rare1
.Lattn_back1:
	s_waitcnt lgkmcnt(5)
	v_mfma_f32_16x16x32_bf16 v[58:61], v[230:233], v[126:129], v[58:61]
	v_exp_f32_e32 v114, v114
	v_exp_f32_e32 v115, v115
	s_waitcnt lgkmcnt(4)
	v_mfma_f32_16x16x32_bf16 v[54:57], v[234:237], v[126:129], v[54:57]
	v_exp_f32_e32 v116, v116
	v_exp_f32_e32 v117, v117
	s_waitcnt lgkmcnt(3)
	v_mfma_f32_16x16x32_bf16 v[50:53], v[238:241], v[126:129], v[50:53]
	v_exp_f32_e32 v118, v118
	v_exp_f32_e32 v119, v119
	v_cvt_pk_bf16_f32 v114, v114, v115
	s_waitcnt lgkmcnt(2)
	v_mfma_f32_16x16x32_bf16 v[46:49], v[242:245], v[126:129], v[46:49]
	v_exp_f32_e32 v120, v120
	v_exp_f32_e32 v121, v121
	v_cvt_pk_bf16_f32 v115, v116, v117
	s_waitcnt lgkmcnt(1)
	v_mfma_f32_16x16x32_bf16 v[42:45], v[246:249], v[126:129], v[42:45]
	v_cvt_pk_bf16_f32 v116, v118, v119
	s_waitcnt lgkmcnt(0)
	v_mfma_f32_16x16x32_bf16 v[34:37], v[250:253], v[126:129], v[34:37]
	v_cvt_pk_bf16_f32 v117, v120, v121
	s_nop 1
	v_mfma_f32_16x16x32_bf16 v[38:41], v[206:209], v[114:117], v[38:41]
	v_exp_f32_e32 v138, v138
	v_mfma_f32_16x16x32_bf16 v[30:33], v[222:225], v[114:117], v[30:33]
	ds_read_b128 v[222:225], v178 offset:9280
	v_exp_f32_e32 v139, v139
	v_mfma_f32_16x16x32_bf16 v[26:29], v[226:229], v[114:117], v[26:29]
	ds_read_b128 v[226:229], v210 offset:11520
	v_exp_f32_e32 v140, v140
	v_mfma_f32_16x16x32_bf16 v[22:25], v[230:233], v[114:117], v[22:25]
	ds_read_b128 v[230:233], v211 offset:13824
	v_exp_f32_e32 v141, v141
	v_mfma_f32_16x16x32_bf16 v[10:13], v[234:237], v[114:117], v[10:13]
	ds_read_b128 v[234:237], v212 offset:16128
	v_exp_f32_e32 v142, v142
	v_mfma_f32_16x16x32_bf16 v[18:21], v[238:241], v[114:117], v[18:21]
	ds_read_b128 v[238:241], v178 offset:18432
	v_exp_f32_e32 v143, v143
	v_cvt_pk_bf16_f32 v130, v138, v139
	v_mfma_f32_16x16x32_bf16 v[14:17], v[242:245], v[114:117], v[14:17]
	ds_read_b128 v[242:245], v178 offset:20752
	v_exp_f32_e32 v144, v144
	v_cvt_pk_bf16_f32 v131, v140, v141
	v_mfma_f32_16x16x32_bf16 v[6:9], v[246:249], v[114:117], v[6:9]
	ds_read_b128 v[246:249], v178 offset:23072
	v_exp_f32_e32 v145, v145
	v_cvt_pk_bf16_f32 v132, v142, v143
	v_mfma_f32_16x16x32_bf16 v[2:5], v[250:253], v[114:117], v[2:5]
	ds_read_b128 v[250:253], v178 offset:25392
	v_cvt_pk_bf16_f32 v133, v144, v145
	s_nop 1
	v_mfma_f32_16x16x32_bf16 v[70:73], v[206:209], v[130:133], v[70:73]
	v_exp_f32_e32 v122, v122
	s_waitcnt lgkmcnt(7)
; #define LAS __attribute__((address_space(3)))
; __device__ __forceinline__ void unit(unsigned char* ws, LAS unsigned char* lds, int b, int h, int mp, int qb, const int tid_in) {
;     ...
;         for (int g = 0; g < 2; ++g) {
;             lacc[g] = __builtin_amdgcn_mfma_f32_16x16x32_bf16(onesf, pf[g][0], lacc[g], 0, 0, 0); lacc[g] = __builtin_amdgcn_mfma_f32_16x16x32_bf16(onesf, pf[g][1], lacc[g], 0, 0, 0); }
; #pragma unroll
;         for (int et = 0; et < 8; ++et) { const LAS bf16_t* vrow = VT + (16 * et + fr) * KP;
;             const bf16x8 vf0 = *(const LAS bf16x8*)(vrow + ((8 * fq + 8 * et) & 63)), vf1 = *(const LAS bf16x8*)(vrow + ((32 + 8 * fq + 8 * et) & 63));
; #pragma unroll
;             for (int g = 0; g < 2; ++g) { o[g][et] = __builtin_amdgcn_mfma_f32_16x16x32_bf16(vf0, pf[g][0], o[g][et], 0, 0, 0); o[g][et] = __builtin_amdgcn_mfma_f32_16x16x32_bf16(vf1, pf[g][1], o[g][et], 0, 0, 0); } }
;         }
;         if (kt + 1 < NT) { FA3_STAGE((kt + 1) & 1); kA = kB; vA0 = vB0; vA1 = vB1;
	v_mfma_f32_16x16x32_bf16 v[66:69], v[222:225], v[130:133], v[66:69]
	v_exp_f32_e32 v123, v123
	s_waitcnt lgkmcnt(6)
	v_mfma_f32_16x16x32_bf16 v[62:65], v[226:229], v[130:133], v[62:65]
	v_exp_f32_e32 v124, v124
	s_waitcnt lgkmcnt(5)
	v_mfma_f32_16x16x32_bf16 v[58:61], v[230:233], v[130:133], v[58:61]
	v_exp_f32_e32 v125, v125
	s_waitcnt lgkmcnt(4)
	v_mfma_f32_16x16x32_bf16 v[54:57], v[234:237], v[130:133], v[54:57]
	v_exp_f32_e32 v134, v134
	s_waitcnt lgkmcnt(3)
	v_mfma_f32_16x16x32_bf16 v[50:53], v[238:241], v[130:133], v[50:53]
	v_exp_f32_e32 v135, v135
	v_cvt_pk_bf16_f32 v118, v122, v123
	s_waitcnt lgkmcnt(2)
	v_mfma_f32_16x16x32_bf16 v[46:49], v[242:245], v[130:133], v[46:49]
	v_exp_f32_e32 v136, v136
	v_cvt_pk_bf16_f32 v119, v124, v125
	s_waitcnt lgkmcnt(1)
	v_mfma_f32_16x16x32_bf16 v[42:45], v[246:249], v[130:133], v[42:45]
	v_exp_f32_e32 v137, v137
	v_cvt_pk_bf16_f32 v120, v134, v135
	s_waitcnt lgkmcnt(0)
	v_mfma_f32_16x16x32_bf16 v[34:37], v[250:253], v[130:133], v[34:37]
	v_cvt_pk_bf16_f32 v121, v136, v137
	s_nop 1
	v_mfma_f32_16x16x32_bf16 v[38:41], v[206:209], v[118:121], v[38:41]
	s_bitcmp1_b32 s68, 0
	s_cselect_b32 s21, 0x6c00, 0
	s_add_i32 s22, s21, 0
	v_mfma_f32_16x16x32_bf16 v[30:33], v[222:225], v[118:121], v[30:33]
	v_add3_u32 v213, s22, v171, v0
	ds_write_b128 v213, v[110:113]
	v_mfma_f32_16x16x32_bf16 v[26:29], v[226:229], v[118:121], v[26:29]
	v_and_b32_e32 v110, 0xffff, v102
	v_add3_u32 v111, s22, v170, v172
	v_lshrrev_b32_e32 v102, 16, v102
	v_mfma_f32_16x16x32_bf16 v[22:25], v[230:233], v[118:121], v[22:25]
	v_lshl_or_b32 v110, v106, 16, v110
	v_and_or_b32 v102, v106, s33, v102
	v_add_u32_e32 v106, 0x2400, v111
	v_mfma_f32_16x16x32_bf16 v[10:13], v[234:237], v[118:121], v[10:13]
	ds_write2_b32 v106, v110, v102 offset1:36
	v_and_b32_e32 v102, 0xffff, v103
	v_lshrrev_b32_e32 v103, 16, v103
	v_mfma_f32_16x16x32_bf16 v[18:21], v[238:241], v[118:121], v[18:21]
	v_lshl_or_b32 v102, v107, 16, v102
	v_and_or_b32 v103, v107, s33, v103
	ds_write2_b32 v106, v102, v103 offset0:72 offset1:108
	v_mfma_f32_16x16x32_bf16 v[14:17], v[242:245], v[118:121], v[14:17]
	v_and_b32_e32 v102, 0xffff, v104
	v_lshrrev_b32_e32 v103, 16, v104
	v_lshl_or_b32 v102, v108, 16, v102
	v_mfma_f32_16x16x32_bf16 v[6:9], v[246:249], v[118:121], v[6:9]
	v_and_or_b32 v103, v108, s33, v103
	ds_write2_b32 v106, v102, v103 offset0:144 offset1:180
	v_and_b32_e32 v102, 0xffff, v105
	v_mfma_f32_16x16x32_bf16 v[2:5], v[250:253], v[118:121], v[2:5]
	v_lshrrev_b32_e32 v103, 16, v105
	v_lshl_or_b32 v102, v109, 16, v102
	v_and_or_b32 v103, v109, s33, v103
	ds_write2_b32 v106, v102, v103 offset0:216 offset1:252
	s_branch .Lattn_stage_b
; __device__ __forceinline__ void unit(unsigned char* ws, LAS unsigned char* lds, int b, int h, int mp, int qb, const int tid_in) {
;     ...
;             if (__any(mx > 8.f)) {
;                 mx = fmaxf(mx, __shfl_xor(mx, 16)); mx = fmaxf(mx, __shfl_xor(mx, 32));
;                 const float dl = fmaxf(mx, 0.f), alpha = __builtin_amdgcn_exp2f(-dl);
;                 m[g] += dl; lacc[g] *= alpha;
; #pragma unroll
;                 for (int jt = 0; jt < 4; ++jt) s[g][jt] -= dl;
; #pragma unroll
;                 for (int et = 0; et < 8; ++et) o[g][et] *= alpha;
;             }
.Lattn_rare0:
	v_and_b32_e32 v182, 64, v187
	v_xor_b32_e32 v181, 16, v187
	v_add_u32_e32 v182, 64, v182
	v_cmp_lt_i32_e32 vcc, v181, v182
	s_nop 1
	v_cndmask_b32_e32 v181, v187, v181, vcc
	v_lshlrev_b32_e32 v181, 2, v181
	ds_bpermute_b32 v181, v181, v180
	v_max_f32_e32 v180, v180, v180
	s_waitcnt lgkmcnt(0)
	v_max_f32_e32 v181, v181, v181
	v_max_f32_e32 v180, v180, v181
	v_xor_b32_e32 v181, 32, v187
	v_cmp_lt_i32_e32 vcc, v181, v182
	s_nop 1
	v_cndmask_b32_e32 v181, v187, v181, vcc
	v_lshlrev_b32_e32 v181, 2, v181
	ds_bpermute_b32 v181, v181, v180
	s_waitcnt lgkmcnt(0)
	v_max3_f32 v181, v180, v181, 0
	v_exp_f32_e64 v180, -v181
	v_add_f32_e32 v175, v175, v181
	v_sub_f32_e32 v126, v126, v181
	v_sub_f32_e32 v127, v127, v181
	v_pk_mul_f32 v[72:73], v[72:73], v[180:181] op_sel_hi:[1,0]
	v_pk_mul_f32 v[70:71], v[70:71], v[180:181] op_sel_hi:[1,0]
	v_sub_f32_e32 v128, v128, v181
	v_sub_f32_e32 v129, v129, v181
	v_sub_f32_e32 v130, v130, v181
	v_sub_f32_e32 v131, v131, v181
	v_sub_f32_e32 v132, v132, v181
	v_sub_f32_e32 v133, v133, v181
	v_sub_f32_e32 v138, v138, v181
	v_sub_f32_e32 v139, v139, v181
	v_sub_f32_e32 v140, v140, v181
	v_sub_f32_e32 v141, v141, v181
	v_sub_f32_e32 v142, v142, v181
	v_sub_f32_e32 v143, v143, v181
	v_sub_f32_e32 v144, v144, v181
	v_sub_f32_e32 v145, v145, v181
	v_pk_mul_f32 v[68:69], v[68:69], v[180:181] op_sel_hi:[1,0]
	v_pk_mul_f32 v[66:67], v[66:67], v[180:181] op_sel_hi:[1,0]
	v_pk_mul_f32 v[64:65], v[64:65], v[180:181] op_sel_hi:[1,0]
	v_pk_mul_f32 v[62:63], v[62:63], v[180:181] op_sel_hi:[1,0]
	v_pk_mul_f32 v[60:61], v[60:61], v[180:181] op_sel_hi:[1,0]
	v_pk_mul_f32 v[58:59], v[58:59], v[180:181] op_sel_hi:[1,0]
	v_pk_mul_f32 v[56:57], v[56:57], v[180:181] op_sel_hi:[1,0]
	v_pk_mul_f32 v[54:55], v[54:55], v[180:181] op_sel_hi:[1,0]
	v_pk_mul_f32 v[52:53], v[52:53], v[180:181] op_sel_hi:[1,0]
	v_pk_mul_f32 v[50:51], v[50:51], v[180:181] op_sel_hi:[1,0]
	v_pk_mul_f32 v[48:49], v[48:49], v[180:181] op_sel_hi:[1,0]
	v_pk_mul_f32 v[46:47], v[46:47], v[180:181] op_sel_hi:[1,0]
	v_pk_mul_f32 v[44:45], v[44:45], v[180:181] op_sel_hi:[1,0]
	v_pk_mul_f32 v[42:43], v[42:43], v[180:181] op_sel_hi:[1,0]
	v_pk_mul_f32 v[36:37], v[36:37], v[180:181] op_sel_hi:[1,0]
	v_pk_mul_f32 v[34:35], v[34:35], v[180:181] op_sel_hi:[1,0]
	s_branch .Lattn_back0
.Lattn_rare1:
	v_and_b32_e32 v182, 64, v187
	v_xor_b32_e32 v181, 16, v187
	v_add_u32_e32 v182, 64, v182
	v_cmp_lt_i32_e32 vcc, v181, v182
	s_nop 1
	v_cndmask_b32_e32 v181, v187, v181, vcc
	v_lshlrev_b32_e32 v181, 2, v181
	ds_bpermute_b32 v181, v181, v180
	v_max_f32_e32 v180, v180, v180
	s_waitcnt lgkmcnt(0)
	v_max_f32_e32 v181, v181, v181
	v_max_f32_e32 v180, v180, v181
	v_xor_b32_e32 v181, 32, v187
	v_cmp_lt_i32_e32 vcc, v181, v182
	s_nop 1
	v_cndmask_b32_e32 v181, v187, v181, vcc
	v_lshlrev_b32_e32 v181, 2, v181
	ds_bpermute_b32 v181, v181, v180
	s_waitcnt lgkmcnt(0)
	v_max3_f32 v181, v180, v181, 0
	v_exp_f32_e64 v180, -v181
	v_add_f32_e32 v177, v177, v181
	v_sub_f32_e32 v114, v114, v181
	v_sub_f32_e32 v115, v115, v181
	v_pk_mul_f32 v[40:41], v[40:41], v[180:181] op_sel_hi:[1,0]
	v_pk_mul_f32 v[38:39], v[38:39], v[180:181] op_sel_hi:[1,0]
	v_sub_f32_e32 v116, v116, v181
	v_sub_f32_e32 v117, v117, v181
	v_sub_f32_e32 v118, v118, v181
	v_sub_f32_e32 v119, v119, v181
	v_sub_f32_e32 v120, v120, v181
	v_sub_f32_e32 v121, v121, v181
	v_sub_f32_e32 v122, v122, v181
	v_sub_f32_e32 v123, v123, v181
	v_sub_f32_e32 v124, v124, v181
	v_sub_f32_e32 v125, v125, v181
	v_sub_f32_e32 v134, v134, v181
	v_sub_f32_e32 v135, v135, v181
	v_sub_f32_e32 v136, v136, v181
	v_sub_f32_e32 v137, v137, v181
	v_pk_mul_f32 v[32:33], v[32:33], v[180:181] op_sel_hi:[1,0]
	v_pk_mul_f32 v[30:31], v[30:31], v[180:181] op_sel_hi:[1,0]
	v_pk_mul_f32 v[28:29], v[28:29], v[180:181] op_sel_hi:[1,0]
	v_pk_mul_f32 v[26:27], v[26:27], v[180:181] op_sel_hi:[1,0]
	v_pk_mul_f32 v[24:25], v[24:25], v[180:181] op_sel_hi:[1,0]
	v_pk_mul_f32 v[22:23], v[22:23], v[180:181] op_sel_hi:[1,0]
	v_pk_mul_f32 v[12:13], v[12:13], v[180:181] op_sel_hi:[1,0]
	v_pk_mul_f32 v[10:11], v[10:11], v[180:181] op_sel_hi:[1,0]
	v_pk_mul_f32 v[20:21], v[20:21], v[180:181] op_sel_hi:[1,0]
	v_pk_mul_f32 v[18:19], v[18:19], v[180:181] op_sel_hi:[1,0]
	v_pk_mul_f32 v[16:17], v[16:17], v[180:181] op_sel_hi:[1,0]
	v_pk_mul_f32 v[14:15], v[14:15], v[180:181] op_sel_hi:[1,0]
	v_pk_mul_f32 v[8:9], v[8:9], v[180:181] op_sel_hi:[1,0]
	v_pk_mul_f32 v[6:7], v[6:7], v[180:181] op_sel_hi:[1,0]
	v_pk_mul_f32 v[4:5], v[4:5], v[180:181] op_sel_hi:[1,0]
	v_pk_mul_f32 v[2:3], v[2:3], v[180:181] op_sel_hi:[1,0]
	s_branch .Lattn_back1
